# pool phase: waves 4-7 take the reversed window group (W=16 pairs with W=2, W=8 with W=4 on each SIMD): balanced VALU load per SIMD
# speedup vs baseline: 1.0093x; 1.0093x over previous
.LBB0_293:
	s_or_b64 exec, exec, s[4:5]
	s_waitcnt lgkmcnt(0)
	v_mov_b32_e32 v0, v170
	v_lshrrev_b32_e32 v1, 8, v0
	v_mul_u32_u24_e32 v1, 0xc0, v1
	v_xor_b32_e32 v0, v0, v1
	s_barrier
	s_xor_b64 s[88:89], s[0:1], -1
	v_ashrrev_i32_e32 v128, 8, v0
	v_cmp_gt_i32_e32 vcc, s29, v128
	s_and_saveexec_b64 s[0:1], vcc
	s_cbranch_execz .LBB0_362
	v_readlane_b32 s44, v252, 4
	s_lshl_b32 s4, s80, 11
	s_mov_b32 s5, s81
	v_readlane_b32 s50, v252, 10
	v_readlane_b32 s51, v252, 11
	v_lshlrev_b32_e32 v0, 3, v0
	s_lshl_b64 s[4:5], s[4:5], 2
	s_mov_b64 s[6:7], s[50:51]
	v_and_b32_e32 v1, 0x7f8, v0
	s_add_u32 s4, s6, s4
	s_addc_u32 s5, s7, s5
	v_lshlrev_b32_e32 v2, 2, v1
	global_load_dwordx4 v[4:7], v2, s[4:5]
	global_load_dwordx4 v[8:11], v2, s[4:5] offset:16
	v_readlane_b32 s56, v252, 16
	v_readlane_b32 s57, v252, 17
	v_readlane_b32 s56, v253, 19
	s_movk_i32 s2, 0x1ff
	v_lshlrev_b32_e32 v2, 1, v1
	v_readlane_b32 s57, v253, 20
	v_bfe_u32 v129, v0, 9, 2
	v_cmp_lt_u32_e64 s[4:5], s2, v1
	v_lshl_add_u64 v[0:1], s[42:43], 0, v[2:3]
	v_lshl_add_u64 v[104:105], s[18:19], 0, v[2:3]
	v_lshl_add_u32 v106, v128, 2, s33
	s_mov_b64 s[6:7], 0
	v_readlane_b32 s45, v252, 5
	v_readlane_b32 s46, v252, 6
	v_readlane_b32 s47, v252, 7
	v_readlane_b32 s48, v252, 8
	v_readlane_b32 s49, v252, 9
	v_readlane_b32 s52, v252, 12
	v_readlane_b32 s53, v252, 13
	v_readlane_b32 s54, v252, 14
	v_readlane_b32 s55, v252, 15
	v_readlane_b32 s58, v252, 18
	v_readlane_b32 s59, v252, 19
	s_branch .LBB0_297
